# sel-attn (P6) both half-step QK sections now use 6-buffer K-fragment rings with counted lgkmcnt, plus diff-attn ring; vgpr alloc 256
# speedup vs baseline: 1.0197x; 1.0161x over previous
; template <int KB, bool SK>
; __device__ __forceinline__ void qkt(f32x16& p0, f32x16& p1, const char* K_lds, int r32, int hi, const bf16x8* qr, bool act) {
;     if (SK && !act) return;
;     p0 = f32x16{}; p1 = f32x16{};
;     const char* kb[4];
; #pragma unroll
;     for (int dd = 0; dd < 4; ++dd) kb[dd] = K_lds + KB * SHM_K + KSWZ(r32, (dd * 16 + hi * 8) * 2);
; #pragma unroll
;     for (int d0 = 0; d0 < 8; ++d0) { const char* a = kb[d0 & 3] + (d0 >> 2) * 128;
;         bf16x8 b0 = *reinterpret_cast<const bf16x8*>(a);
;         bf16x8 b1 = *reinterpret_cast<const bf16x8*>(a + 32 * 256);
;         p0 = __builtin_amdgcn_mfma_f32_32x32x16_bf16(b0, qr[d0], p0, 0, 0, 0);
;         p1 = __builtin_amdgcn_mfma_f32_32x32x16_bf16(b1, qr[d0], p1, 0, 0, 0); }
; }
.LBB0_1332:
	s_waitcnt vmcnt(3)
	v_cndmask_b32_e64 v2, 0, 1, s[82:83]
	v_cmp_ne_u32_e64 s[4:5], 1, v2
	s_andn2_b64 vcc, exec, s[82:83]
	s_cbranch_vccnz .LBB0_1334
	ds_read_b128 v[2:5], v239 offset:49152
	ds_read_b128 v[6:9], v239 offset:57344
	ds_read_b128 v[10:13], v240 offset:49152
	ds_read_b128 v[144:147], v240 offset:57344
	ds_read_b128 v[148:151], v241 offset:49152
	ds_read_b128 v[152:155], v241 offset:57344
	s_waitcnt lgkmcnt(5)
	v_mfma_f32_32x32x16_bf16 v[112:127], v[2:5], v[188:191], 0
	ds_read_b128 v[2:5], v242 offset:49152
	s_waitcnt lgkmcnt(5)
	v_mfma_f32_32x32x16_bf16 v[80:95], v[6:9], v[188:191], 0
	ds_read_b128 v[6:9], v242 offset:57344
	s_waitcnt lgkmcnt(5)
	v_mfma_f32_32x32x16_bf16 v[112:127], v[10:13], v[184:187], v[112:127]
	ds_read_b128 v[10:13], v239 offset:49280
	s_waitcnt lgkmcnt(5)
	v_mfma_f32_32x32x16_bf16 v[80:95], v[144:147], v[184:187], v[80:95]
	ds_read_b128 v[144:147], v239 offset:57472
	s_waitcnt lgkmcnt(5)
	v_mfma_f32_32x32x16_bf16 v[112:127], v[148:151], v[180:183], v[112:127]
	ds_read_b128 v[148:151], v240 offset:49280
	s_waitcnt lgkmcnt(5)
	v_mfma_f32_32x32x16_bf16 v[80:95], v[152:155], v[180:183], v[80:95]
	ds_read_b128 v[152:155], v240 offset:57472
	s_waitcnt lgkmcnt(5)
	v_mfma_f32_32x32x16_bf16 v[112:127], v[2:5], v[176:179], v[112:127]
	ds_read_b128 v[2:5], v241 offset:49280
	s_waitcnt lgkmcnt(5)
	v_mfma_f32_32x32x16_bf16 v[80:95], v[6:9], v[176:179], v[80:95]
	ds_read_b128 v[6:9], v241 offset:57472
	s_waitcnt lgkmcnt(5)
	v_mfma_f32_32x32x16_bf16 v[112:127], v[10:13], v[172:175], v[112:127]
	ds_read_b128 v[10:13], v242 offset:49280
	s_waitcnt lgkmcnt(5)
	v_mfma_f32_32x32x16_bf16 v[80:95], v[144:147], v[172:175], v[80:95]
	ds_read_b128 v[144:147], v242 offset:57472
	s_waitcnt lgkmcnt(5)
	v_mfma_f32_32x32x16_bf16 v[112:127], v[148:151], v[168:171], v[112:127]
	s_waitcnt lgkmcnt(4)
	v_mfma_f32_32x32x16_bf16 v[80:95], v[152:155], v[168:171], v[80:95]
	s_waitcnt lgkmcnt(3)
	v_mfma_f32_32x32x16_bf16 v[112:127], v[2:5], v[164:167], v[112:127]
	s_waitcnt lgkmcnt(2)
	v_mfma_f32_32x32x16_bf16 v[80:95], v[6:9], v[164:167], v[80:95]
	s_waitcnt lgkmcnt(1)
	v_mfma_f32_32x32x16_bf16 v[112:127], v[10:13], v[160:163], v[112:127]
	s_waitcnt lgkmcnt(0)
	v_mfma_f32_32x32x16_bf16 v[80:95], v[144:147], v[160:163], v[80:95]

; template <int KB, bool SK>
; __device__ __forceinline__ void qkt(f32x16& p0, f32x16& p1, const char* K_lds, int r32, int hi, const bf16x8* qr, bool act) {
;     if (SK && !act) return;
;     p0 = f32x16{}; p1 = f32x16{};
;     const char* kb[4];
; #pragma unroll
;     for (int dd = 0; dd < 4; ++dd) kb[dd] = K_lds + KB * SHM_K + KSWZ(r32, (dd * 16 + hi * 8) * 2);
; #pragma unroll
;     for (int d0 = 0; d0 < 8; ++d0) { const char* a = kb[d0 & 3] + (d0 >> 2) * 128;
;         bf16x8 b0 = *reinterpret_cast<const bf16x8*>(a);
;         bf16x8 b1 = *reinterpret_cast<const bf16x8*>(a + 32 * 256);
;         p0 = __builtin_amdgcn_mfma_f32_32x32x16_bf16(b0, qr[d0], p0, 0, 0, 0);
;         p1 = __builtin_amdgcn_mfma_f32_32x32x16_bf16(b1, qr[d0], p1, 0, 0, 0); }
; }
.LBB0_1382:
	v_cndmask_b32_e64 v15, 0, 1, s[84:85]
	v_cmp_ne_u32_e64 s[6:7], 1, v15
	s_andn2_b64 vcc, exec, s[84:85]
	s_cbranch_vccnz .LBB0_1384
	ds_read_b128 v[144:147], v239 offset:32768
	ds_read_b128 v[148:151], v239 offset:40960
	ds_read_b128 v[152:155], v240 offset:32768
	ds_read_b128 v[156:159], v240 offset:40960
	ds_read_b128 v[244:247], v241 offset:32768
	ds_read_b128 v[252:255], v241 offset:40960
	s_waitcnt lgkmcnt(5)
	v_mfma_f32_32x32x16_bf16 v[128:143], v[144:147], v[188:191], 0
	ds_read_b128 v[144:147], v242 offset:32768
	s_waitcnt lgkmcnt(5)
	v_mfma_f32_32x32x16_bf16 v[96:111], v[148:151], v[188:191], 0
	ds_read_b128 v[148:151], v242 offset:40960
	s_waitcnt lgkmcnt(5)
	v_mfma_f32_32x32x16_bf16 v[128:143], v[152:155], v[184:187], v[128:143]
	ds_read_b128 v[152:155], v239 offset:32896
	s_waitcnt lgkmcnt(5)
	v_mfma_f32_32x32x16_bf16 v[96:111], v[156:159], v[184:187], v[96:111]
	ds_read_b128 v[156:159], v239 offset:41088
	s_waitcnt lgkmcnt(5)
	v_mfma_f32_32x32x16_bf16 v[128:143], v[244:247], v[180:183], v[128:143]
	ds_read_b128 v[244:247], v240 offset:32896
	s_waitcnt lgkmcnt(5)
	v_mfma_f32_32x32x16_bf16 v[96:111], v[252:255], v[180:183], v[96:111]
	ds_read_b128 v[252:255], v240 offset:41088
	s_waitcnt lgkmcnt(5)
	v_mfma_f32_32x32x16_bf16 v[128:143], v[144:147], v[176:179], v[128:143]
	ds_read_b128 v[144:147], v241 offset:32896
	s_waitcnt lgkmcnt(5)
	v_mfma_f32_32x32x16_bf16 v[96:111], v[148:151], v[176:179], v[96:111]
	ds_read_b128 v[148:151], v241 offset:41088
	s_waitcnt lgkmcnt(5)
	v_mfma_f32_32x32x16_bf16 v[128:143], v[152:155], v[172:175], v[128:143]
	ds_read_b128 v[152:155], v242 offset:32896
	s_waitcnt lgkmcnt(5)
	v_mfma_f32_32x32x16_bf16 v[96:111], v[156:159], v[172:175], v[96:111]
	ds_read_b128 v[156:159], v242 offset:41088
	s_waitcnt lgkmcnt(5)
	v_mfma_f32_32x32x16_bf16 v[128:143], v[244:247], v[168:171], v[128:143]
	s_waitcnt lgkmcnt(4)
	v_mfma_f32_32x32x16_bf16 v[96:111], v[252:255], v[168:171], v[96:111]
	s_waitcnt lgkmcnt(3)
	v_mfma_f32_32x32x16_bf16 v[128:143], v[144:147], v[164:167], v[128:143]
	s_waitcnt lgkmcnt(2)
	v_mfma_f32_32x32x16_bf16 v[96:111], v[148:151], v[164:167], v[96:111]
	s_waitcnt lgkmcnt(1)
	v_mfma_f32_32x32x16_bf16 v[128:143], v[152:155], v[160:163], v[128:143]
	s_waitcnt lgkmcnt(0)
	v_mfma_f32_32x32x16_bf16 v[96:111], v[156:159], v[160:163], v[96:111]

; __global__ void __launch_bounds__(512, 2) mega_fwd(Args args) {
;     extern __shared__ __attribute__((aligned(16))) unsigned char lds[];
	.amdhsa_kernel _Z8mega_fwd4Args
		.amdhsa_group_segment_fixed_size 0
		.amdhsa_private_segment_fixed_size 0
		.amdhsa_kernarg_size 456
		.amdhsa_user_sgpr_count 2
		.amdhsa_user_sgpr_dispatch_ptr 0
		.amdhsa_user_sgpr_queue_ptr 0
		.amdhsa_user_sgpr_kernarg_segment_ptr 1
		.amdhsa_user_sgpr_dispatch_id 0
		.amdhsa_user_sgpr_kernarg_preload_length 0
		.amdhsa_user_sgpr_kernarg_preload_offset 0
		.amdhsa_user_sgpr_private_segment_size 0
		.amdhsa_uses_dynamic_stack 0
		.amdhsa_enable_private_segment 0
		.amdhsa_system_sgpr_workgroup_id_x 1
		.amdhsa_system_sgpr_workgroup_id_y 0
		.amdhsa_system_sgpr_workgroup_id_z 0
		.amdhsa_system_sgpr_workgroup_info 0
		.amdhsa_system_vgpr_workitem_id 2
		.amdhsa_next_free_vgpr 256
		.amdhsa_next_free_sgpr 98
		.amdhsa_accum_offset 256
		.amdhsa_reserve_vcc 1
		.amdhsa_float_round_mode_32 0
		.amdhsa_float_round_mode_16_64 0
		.amdhsa_float_denorm_mode_32 3
		.amdhsa_float_denorm_mode_16_64 3
		.amdhsa_dx10_clamp 1
		.amdhsa_ieee_mode 1
		.amdhsa_fp16_overflow 0
		.amdhsa_tg_split 0
		.amdhsa_exception_fp_ieee_invalid_op 0
		.amdhsa_exception_fp_denorm_src 0
		.amdhsa_exception_fp_ieee_div_zero 0
		.amdhsa_exception_fp_ieee_overflow 0
		.amdhsa_exception_fp_ieee_underflow 0
		.amdhsa_exception_fp_ieee_inexact 0
		.amdhsa_exception_int_div_zero 0
	.end_amdhsa_kernel

; __global__ void __launch_bounds__(512, 2) mega_fwd(Args args) {
amdhsa.kernels:
  - .agpr_count:     0
    .args:
      - .offset:         0
        .size:           200
        .value_kind:     by_value
      - .offset:         200
        .size:           4
        .value_kind:     hidden_block_count_x
      - .offset:         204
        .size:           4
        .value_kind:     hidden_block_count_y
      - .offset:         208
        .size:           4
        .value_kind:     hidden_block_count_z
      - .offset:         212
        .size:           2
        .value_kind:     hidden_group_size_x
      - .offset:         214
        .size:           2
        .value_kind:     hidden_group_size_y
      - .offset:         216
        .size:           2
        .value_kind:     hidden_group_size_z
      - .offset:         218
        .size:           2
        .value_kind:     hidden_remainder_x
      - .offset:         220
        .size:           2
        .value_kind:     hidden_remainder_y
      - .offset:         222
        .size:           2
        .value_kind:     hidden_remainder_z
      - .offset:         240
        .size:           8
        .value_kind:     hidden_global_offset_x
      - .offset:         248
        .size:           8
        .value_kind:     hidden_global_offset_y
      - .offset:         256
        .size:           8
        .value_kind:     hidden_global_offset_z
      - .offset:         264
        .size:           2
        .value_kind:     hidden_grid_dims
      - .offset:         288
        .size:           8
        .value_kind:     hidden_multigrid_sync_arg
      - .offset:         320
        .size:           4
        .value_kind:     hidden_dynamic_lds_size
    .group_segment_fixed_size: 0
    .kernarg_segment_align: 8
    .kernarg_segment_size: 456
    .language:       OpenCL C
    .language_version:
      - 2
      - 0
    .max_flat_workgroup_size: 512
    .name:           _Z8mega_fwd4Args
    .private_segment_fixed_size: 0
    .sgpr_count:     104
    .sgpr_spill_count: 65
    .symbol:         _Z8mega_fwd4Args.kd
    .uniform_work_group_size: 1
    .uses_dynamic_stack: false
    .vgpr_count:     256
    .vgpr_spill_count: 0
    .wavefront_size: 64
